# grid-barrier spin loops poll without s_sleep (A/B on top of v70)
# speedup vs baseline: 1.1675x; 1.1675x over previous
; __device__ __forceinline__ unsigned xb_ld(unsigned* p)              { return __hip_atomic_load(p, __ATOMIC_RELAXED, __HIP_MEMORY_SCOPE_AGENT); }
; __device__ __forceinline__ void xcd_barrier_complete(unsigned* bar, unsigned x, unsigned& nloc, unsigned& nx) {
;     const unsigned G = gridDim.x * gridDim.y * gridDim.z;
;     unsigned sum, cnt, mine, sp = 0u;
;     for (;;) {
;         sum = 0u; cnt = 0u; mine = 0u;
; #pragma unroll
;         for (unsigned j = 0; j < 16; ++j) { const unsigned c = xb_ld(&bar[XB_XCNT(j)]); sum += c; cnt += (c > 0u) ? 1u : 0u; mine = (j == x) ? c : mine; }
;         if (sum == G) break;
;         __builtin_amdgcn_s_sleep(1);
;         if ((++sp & 255u) == 0u) { if (xb_ld(&bar[XB_TMO])) break; if (sp > XB_SPIN_CAP) { atomicAdd(&bar[XB_TMO], 1u); break; } }
;     }
;     nloc = mine > 0u ? mine : 1u; nx = cnt > 0u ? cnt : 1u;
; }
.LBB0_79:
	global_load_dword v17, v18, s[6:7] sc1
	s_waitcnt lgkmcnt(0)
	global_load_dword v0, v18, s[8:9] sc1
	global_load_dword v1, v18, s[10:11] sc1
	global_load_dword v4, v18, s[12:13] sc1
	global_load_dword v5, v18, s[14:15] sc1
	global_load_dword v6, v18, s[16:17] sc1
	global_load_dword v7, v18, s[18:19] sc1
	global_load_dword v8, v18, s[20:21] sc1
	global_load_dword v9, v18, s[22:23] sc1
	global_load_dword v10, v18, s[24:25] sc1
	global_load_dword v11, v18, s[26:27] sc1
	global_load_dword v12, v18, s[28:29] sc1
	global_load_dword v13, v18, s[30:31] sc1
	global_load_dword v14, v18, s[34:35] sc1
	global_load_dword v15, v18, s[36:37] sc1
	global_load_dword v16, v18, s[38:39] sc1
	s_mov_b64 s[40:41], -1
	s_mov_b64 s[42:43], -1
	s_waitcnt vmcnt(14)
	v_add_u32_e32 v19, v0, v17
	s_waitcnt vmcnt(13)
	v_add_u32_e32 v19, v19, v1
	s_waitcnt vmcnt(12)
	v_add_u32_e32 v19, v19, v4
	s_waitcnt vmcnt(11)
	v_add_u32_e32 v19, v19, v5
	s_waitcnt vmcnt(10)
	v_add_u32_e32 v19, v19, v6
	s_waitcnt vmcnt(9)
	v_add_u32_e32 v19, v19, v7
	s_waitcnt vmcnt(8)
	v_add_u32_e32 v19, v19, v8
	s_waitcnt vmcnt(7)
	v_add_u32_e32 v19, v19, v9
	s_waitcnt vmcnt(6)
	v_add_u32_e32 v19, v19, v10
	s_waitcnt vmcnt(5)
	v_add_u32_e32 v19, v19, v11
	s_waitcnt vmcnt(4)
	v_add_u32_e32 v19, v19, v12
	s_waitcnt vmcnt(3)
	v_add_u32_e32 v19, v19, v13
	s_waitcnt vmcnt(2)
	v_add_u32_e32 v19, v19, v14
	s_waitcnt vmcnt(1)
	v_add_u32_e32 v19, v19, v15
	s_waitcnt vmcnt(0)
	v_add_u32_e32 v19, v19, v16
	v_cmp_eq_u32_e32 vcc, s49, v19
	s_cbranch_vccnz .LBB0_78
	s_and_b32 s40, s50, 0xff
	s_cmp_eq_u32 s40, 0
	s_mov_b64 s[40:41], -1
	s_mov_b64 s[44:45], -1
	s_nop 0
	s_cbranch_scc1 .LBB0_83
	s_and_b64 vcc, exec, s[44:45]
	s_cbranch_vccz .LBB0_78

; __device__ __forceinline__ unsigned xb_ld(unsigned* p)              { return __hip_atomic_load(p, __ATOMIC_RELAXED, __HIP_MEMORY_SCOPE_AGENT); }
; __device__ __forceinline__ unsigned xb_add(unsigned* p, unsigned v) { return __hip_atomic_fetch_add(p, v, __ATOMIC_RELAXED, __HIP_MEMORY_SCOPE_AGENT); }
; #define XB_SPIN(cond, bar) do { unsigned _sp = 0; while (cond) { __builtin_amdgcn_s_sleep(1); \
;     if ((++_sp & 255u) == 0u) { if (xb_ld(&(bar)[XB_TMO])) break; if (_sp > XB_SPIN_CAP) { atomicAdd(&(bar)[XB_TMO], 1u); break; } } } } while (0)
; __device__ __forceinline__ void xcd_barrier(const XcdBarrier& b) {
;     ...
;             else XB_SPIN(xb_ld(&bar[XB_TOPGEN]) == tg, bar);
;             __builtin_amdgcn_fence(__ATOMIC_ACQUIRE, "agent");
;             xb_add(&bar[XB_XGEN(b.x)], 1u);
;             asm volatile("s_waitcnt vmcnt(0)" ::: "memory");
;         } else {
;             XB_SPIN(xb_ld(&bar[XB_XGEN(b.x)]) == gen, bar);
.LBB0_97:
	s_and_b32 s20, s24, 0xff
	s_mov_b64 s[18:19], -1
	s_cmp_lg_u32 s20, 0
	s_mov_b64 s[22:23], -1
	s_nop 0
	s_cbranch_scc0 .LBB0_100
	s_and_b64 vcc, exec, s[22:23]
	s_cbranch_vccz .LBB0_96

; __device__ __forceinline__ unsigned xb_ld(unsigned* p)              { return __hip_atomic_load(p, __ATOMIC_RELAXED, __HIP_MEMORY_SCOPE_AGENT); }
; __device__ __forceinline__ unsigned xb_add(unsigned* p, unsigned v) { return __hip_atomic_fetch_add(p, v, __ATOMIC_RELAXED, __HIP_MEMORY_SCOPE_AGENT); }
; #define XB_SPIN(cond, bar) do { unsigned _sp = 0; while (cond) { __builtin_amdgcn_s_sleep(1); \
;     if ((++_sp & 255u) == 0u) { if (xb_ld(&(bar)[XB_TMO])) break; if (_sp > XB_SPIN_CAP) { atomicAdd(&(bar)[XB_TMO], 1u); break; } } } } while (0)
; __device__ __forceinline__ void xcd_barrier(const XcdBarrier& b) {
;     ...
;             else XB_SPIN(xb_ld(&bar[XB_TOPGEN]) == tg, bar);
;             __builtin_amdgcn_fence(__ATOMIC_ACQUIRE, "agent");
;             xb_add(&bar[XB_XGEN(b.x)], 1u);
;             asm volatile("s_waitcnt vmcnt(0)" ::: "memory");
;         } else {
;             XB_SPIN(xb_ld(&bar[XB_XGEN(b.x)]) == gen, bar);
.LBB0_114:
	s_and_b32 s16, s22, 0xff
	s_cmp_lg_u32 s16, 0
	s_mov_b64 s[18:19], -1
	s_nop 0
	s_cbranch_scc0 .LBB0_117
	s_mov_b64 s[20:21], -1
	s_and_b64 vcc, exec, s[18:19]
	s_cbranch_vccz .LBB0_113

.LBB0_257:
	s_nop 0
	global_load_dword v1, v146, s[2:3] offset:32 sc1
	s_waitcnt vmcnt(0)
	v_and_b32_e32 v1, 0xffff0000, v1
	v_cmp_ne_u32_e32 vcc, v1, v0
	s_or_b64 s[4:5], vcc, s[4:5]
	s_andn2_b64 exec, exec, s[4:5]
	s_cbranch_execnz .LBB0_257

; __device__ __forceinline__ unsigned xb_ld(unsigned* p)              { return __hip_atomic_load(p, __ATOMIC_RELAXED, __HIP_MEMORY_SCOPE_AGENT); }
; __device__ __forceinline__ void xcd_barrier_complete(unsigned* bar, unsigned x, unsigned& nloc, unsigned& nx) {
;     ...
;     for (;;) {
;         sum = 0u; cnt = 0u; mine = 0u;
; #pragma unroll
;         for (unsigned j = 0; j < 16; ++j) { const unsigned c = xb_ld(&bar[XB_XCNT(j)]); sum += c; cnt += (c > 0u) ? 1u : 0u; mine = (j == x) ? c : mine; }
;         if (sum == G) break;
;         __builtin_amdgcn_s_sleep(1);
;         if ((++sp & 255u) == 0u) { if (xb_ld(&bar[XB_TMO])) break; if (sp > XB_SPIN_CAP) { atomicAdd(&bar[XB_TMO], 1u); break; } }
;     }
.LBB0_264:
	global_load_dword v15, v146, s[6:7] sc1
	s_waitcnt lgkmcnt(0)
	global_load_dword v0, v146, s[8:9] sc1
	global_load_dword v1, v146, s[10:11] sc1
	global_load_dword v2, v146, s[12:13] sc1
	global_load_dword v3, v146, s[14:15] sc1
	global_load_dword v4, v146, s[16:17] sc1
	global_load_dword v5, v146, s[18:19] sc1
	global_load_dword v6, v146, s[20:21] sc1
	global_load_dword v7, v146, s[22:23] sc1
	global_load_dword v8, v146, s[24:25] sc1
	global_load_dword v9, v146, s[26:27] sc1
	global_load_dword v10, v146, s[28:29] sc1
	global_load_dword v11, v146, s[30:31] sc1
	global_load_dword v12, v146, s[34:35] sc1
	global_load_dword v13, v146, s[36:37] sc1
	global_load_dword v14, v146, s[38:39] sc1
	s_mov_b64 s[40:41], -1
	s_mov_b64 s[42:43], -1
	s_waitcnt vmcnt(14)
	v_add_u32_e32 v16, v0, v15
	s_waitcnt vmcnt(13)
	v_add_u32_e32 v16, v16, v1
	s_waitcnt vmcnt(12)
	v_add_u32_e32 v16, v16, v2
	s_waitcnt vmcnt(11)
	v_add_u32_e32 v16, v16, v3
	s_waitcnt vmcnt(10)
	v_add_u32_e32 v16, v16, v4
	s_waitcnt vmcnt(9)
	v_add_u32_e32 v16, v16, v5
	s_waitcnt vmcnt(8)
	v_add_u32_e32 v16, v16, v6
	s_waitcnt vmcnt(7)
	v_add_u32_e32 v16, v16, v7
	s_waitcnt vmcnt(6)
	v_add_u32_e32 v16, v16, v8
	s_waitcnt vmcnt(5)
	v_add_u32_e32 v16, v16, v9
	s_waitcnt vmcnt(4)
	v_add_u32_e32 v16, v16, v10
	s_waitcnt vmcnt(3)
	v_add_u32_e32 v16, v16, v11
	s_waitcnt vmcnt(2)
	v_add_u32_e32 v16, v16, v12
	s_waitcnt vmcnt(1)
	v_add_u32_e32 v16, v16, v13
	s_waitcnt vmcnt(0)
	v_add_u32_e32 v16, v16, v14
	v_cmp_eq_u32_e32 vcc, s63, v16
	s_cbranch_vccnz .LBB0_263
	s_and_b32 s40, s46, 0xff
	s_cmp_eq_u32 s40, 0
	s_mov_b64 s[40:41], -1
	s_mov_b64 s[44:45], -1
	s_nop 0
	s_cbranch_scc1 .LBB0_268
	s_and_b64 vcc, exec, s[44:45]
	s_cbranch_vccz .LBB0_263

; __device__ __forceinline__ unsigned xb_ld(unsigned* p)              { return __hip_atomic_load(p, __ATOMIC_RELAXED, __HIP_MEMORY_SCOPE_AGENT); }
; __device__ __forceinline__ unsigned xb_add(unsigned* p, unsigned v) { return __hip_atomic_fetch_add(p, v, __ATOMIC_RELAXED, __HIP_MEMORY_SCOPE_AGENT); }
; #define XB_SPIN(cond, bar) do { unsigned _sp = 0; while (cond) { __builtin_amdgcn_s_sleep(1); \
;     if ((++_sp & 255u) == 0u) { if (xb_ld(&(bar)[XB_TMO])) break; if (_sp > XB_SPIN_CAP) { atomicAdd(&(bar)[XB_TMO], 1u); break; } } } } while (0)
; __device__ __forceinline__ void xcd_barrier(const XcdBarrier& b) {
;     ...
;             else XB_SPIN(xb_ld(&bar[XB_TOPGEN]) == tg, bar);
;             __builtin_amdgcn_fence(__ATOMIC_ACQUIRE, "agent");
;             xb_add(&bar[XB_XGEN(b.x)], 1u);
;             asm volatile("s_waitcnt vmcnt(0)" ::: "memory");
;         } else {
;             XB_SPIN(xb_ld(&bar[XB_XGEN(b.x)]) == gen, bar);
.LBB0_299:
	s_and_b32 s18, s22, 0xff
	s_mov_b64 s[16:17], -1
	s_cmp_lg_u32 s18, 0
	s_mov_b64 s[20:21], -1
	s_nop 0
	s_cbranch_scc0 .LBB0_302
	s_and_b64 vcc, exec, s[20:21]
	s_cbranch_vccz .LBB0_298

; __device__ __forceinline__ unsigned xb_ld(unsigned* p)              { return __hip_atomic_load(p, __ATOMIC_RELAXED, __HIP_MEMORY_SCOPE_AGENT); }
; __device__ __forceinline__ void xcd_barrier_complete(unsigned* bar, unsigned x, unsigned& nloc, unsigned& nx) {
;     ...
;     for (;;) {
;         sum = 0u; cnt = 0u; mine = 0u;
; #pragma unroll
;         for (unsigned j = 0; j < 16; ++j) { const unsigned c = xb_ld(&bar[XB_XCNT(j)]); sum += c; cnt += (c > 0u) ? 1u : 0u; mine = (j == x) ? c : mine; }
;         if (sum == G) break;
;         __builtin_amdgcn_s_sleep(1);
;         if ((++sp & 255u) == 0u) { if (xb_ld(&bar[XB_TMO])) break; if (sp > XB_SPIN_CAP) { atomicAdd(&bar[XB_TMO], 1u); break; } }
;     }
.LBB0_832:
	global_load_dword v15, v146, s[6:7] sc1
	s_waitcnt lgkmcnt(0)
	global_load_dword v0, v146, s[8:9] sc1
	global_load_dword v1, v146, s[10:11] sc1
	global_load_dword v2, v146, s[12:13] sc1
	global_load_dword v3, v146, s[14:15] sc1
	global_load_dword v4, v146, s[16:17] sc1
	global_load_dword v5, v146, s[18:19] sc1
	global_load_dword v6, v146, s[20:21] sc1
	global_load_dword v7, v146, s[22:23] sc1
	global_load_dword v8, v146, s[24:25] sc1
	global_load_dword v9, v146, s[26:27] sc1
	global_load_dword v10, v146, s[28:29] sc1
	global_load_dword v11, v146, s[30:31] sc1
	global_load_dword v12, v146, s[34:35] sc1
	global_load_dword v13, v146, s[36:37] sc1
	global_load_dword v14, v146, s[38:39] sc1
	s_mov_b64 s[40:41], -1
	s_mov_b64 s[42:43], -1
	s_waitcnt vmcnt(14)
	v_add_u32_e32 v16, v0, v15
	s_waitcnt vmcnt(13)
	v_add_u32_e32 v16, v16, v1
	s_waitcnt vmcnt(12)
	v_add_u32_e32 v16, v16, v2
	s_waitcnt vmcnt(11)
	v_add_u32_e32 v16, v16, v3
	s_waitcnt vmcnt(10)
	v_add_u32_e32 v16, v16, v4
	s_waitcnt vmcnt(9)
	v_add_u32_e32 v16, v16, v5
	s_waitcnt vmcnt(8)
	v_add_u32_e32 v16, v16, v6
	s_waitcnt vmcnt(7)
	v_add_u32_e32 v16, v16, v7
	s_waitcnt vmcnt(6)
	v_add_u32_e32 v16, v16, v8
	s_waitcnt vmcnt(5)
	v_add_u32_e32 v16, v16, v9
	s_waitcnt vmcnt(4)
	v_add_u32_e32 v16, v16, v10
	s_waitcnt vmcnt(3)
	v_add_u32_e32 v16, v16, v11
	s_waitcnt vmcnt(2)
	v_add_u32_e32 v16, v16, v12
	s_waitcnt vmcnt(1)
	v_add_u32_e32 v16, v16, v13
	s_waitcnt vmcnt(0)
	v_add_u32_e32 v16, v16, v14
	v_cmp_eq_u32_e32 vcc, s63, v16
	s_cbranch_vccnz .LBB0_831
	s_and_b32 s40, s47, 0xff
	s_cmp_eq_u32 s40, 0
	s_mov_b64 s[40:41], -1
	s_mov_b64 s[44:45], -1
	s_nop 0
	s_cbranch_scc1 .LBB0_836
	s_and_b64 vcc, exec, s[44:45]
	s_cbranch_vccz .LBB0_831
